# P7b conv-halo fix-up: straight-line per-unit code, all loads of a lane's items issued up front (one round trip per unit instead of six)
# speedup vs baseline: 1.0200x; 1.0029x over previous
; #define tid  (fresh_tid_w(wave_s))
; __global__ void __launch_bounds__(512, 2) fwd_megakernel(Args a) {
;     ...
;         { const float* cw = a.in[I_CONVW] + (size_t)l * 3 * FF2; pg8::StaticOrder S; S.init(M, D, G, bx); pg8::Unit uu; const int t_ = tid;
;           for (int i = 0; S.next(i, uu); ++i) { const int pm = uu.pm; if ((pm & 31) == 0) continue;
;             for (int it = t_; it < 2 * (FF / 4); it += 512) { const int c4 = it % (FF / 4), rr = it / (FF / 4);
;               const int col = c4 * 4;
;               f32x4 hg = *(const f32x4*)(HC0 + (size_t)(pm * 2 + rr) * FF2 + col), hv = *(const f32x4*)(HC0 + (size_t)(pm * 2 + rr) * FF2 + FF + col);
;               const f32x4 x1g = *(const f32x4*)(RAWH + (size_t)((pm - 1) * 2 + 1) * FF2 + col), x1v = *(const f32x4*)(RAWH + (size_t)((pm - 1) * 2 + 1) * FF2 + FF + col);
;               const f32x4 x2g = *(const f32x4*)(RAWH + (size_t)((pm - 1) * 2) * FF2 + col), x2v = *(const f32x4*)(RAWH + (size_t)((pm - 1) * 2) * FF2 + FF + col);
;               const f32x4 w0g = *(const f32x4*)(cw + col), w0v = *(const f32x4*)(cw + FF + col), w1g = *(const f32x4*)(cw + FF2 + col), w1v = *(const f32x4*)(cw + FF2 + FF + col);
.LBB0_1007:
	s_and_b32 s2, s31, 31
	s_cmp_lg_u32 s2, 0
	s_cselect_b64 s[8:9], -1, 0
	s_and_b64 s[8:9], s[8:9], s[10:11]
	s_and_saveexec_b64 s[12:13], s[8:9]
	s_cbranch_execz .LBB0_998
	s_lshl_b32 s8, s31, 1
	s_mul_i32 s20, s8, 0x5800
	s_add_u32 s2, s20, 0x6500000
	s_add_u32 s9, s2, 0x5800
	s_add_u32 s21, s20, 0x58fa800
	s_add_u32 s22, s20, 0x58f5000
	s_lshl_b32 s23, s31, 8
	s_mul_i32 s23, s23, 0x1600
	s_add_u32 s23, s23, 0xf100000
	s_add_u32 s24, s23, 0x1600
	v_lshlrev_b32_e32 v0, 4, v40
	v_add_u32_e32 v1, s2, v0
	v_add_u32_e32 v3, s21, v0
	v_add_u32_e32 v2, 0x2c00, v1
	v_add_u32_e32 v4, 0x2c00, v3
	global_load_dwordx4 v[64:67], v1, s[58:59]
	global_load_dwordx4 v[68:71], v2, s[58:59]
	global_load_dwordx4 v[72:75], v3, s[58:59]
	global_load_dwordx4 v[76:79], v4, s[58:59]
	global_load_dwordx4 v[88:91], v0, s[14:15]
	global_load_dwordx4 v[92:95], v0, s[0:1]
	v_add_u32_e32 v5, s22, v0
	v_add_u32_e32 v6, 0x2c00, v5
	global_load_dwordx4 v[80:83], v5, s[58:59]
	global_load_dwordx4 v[84:87], v6, s[58:59]
	global_load_dwordx4 v[96:99], v0, s[16:17]
	global_load_dwordx4 v[100:103], v0, s[4:5]
	s_cmp_lt_u32 s93, 192
	s_cbranch_scc0 .Lp7b_l1r
	v_add_u32_e32 v0, 512, v40
	v_lshlrev_b32_e32 v0, 4, v0
	v_add_u32_e32 v1, s2, v0
	v_add_u32_e32 v3, s21, v0
	v_add_u32_e32 v2, 0x2c00, v1
	v_add_u32_e32 v4, 0x2c00, v3
	global_load_dwordx4 v[104:107], v1, s[58:59]
	global_load_dwordx4 v[108:111], v2, s[58:59]
	global_load_dwordx4 v[112:115], v3, s[58:59]
	global_load_dwordx4 v[116:119], v4, s[58:59]
	global_load_dwordx4 v[128:131], v0, s[14:15]
	global_load_dwordx4 v[132:135], v0, s[0:1]
	v_add_u32_e32 v5, s22, v0
	v_add_u32_e32 v6, 0x2c00, v5
	global_load_dwordx4 v[120:123], v5, s[58:59]
	global_load_dwordx4 v[124:127], v6, s[58:59]
	global_load_dwordx4 v[136:139], v0, s[16:17]
	global_load_dwordx4 v[140:143], v0, s[4:5]
	s_branch .Lp7b_l2
.Lp7b_l1r:
	v_subrev_u32_e32 v0, 192, v40
	v_lshlrev_b32_e32 v0, 4, v0
	v_add_u32_e32 v1, s9, v0
	v_add_u32_e32 v3, s21, v0
	v_add_u32_e32 v2, 0x2c00, v1
	v_add_u32_e32 v4, 0x2c00, v3
	global_load_dwordx4 v[104:107], v1, s[58:59]
	global_load_dwordx4 v[108:111], v2, s[58:59]
	global_load_dwordx4 v[112:115], v3, s[58:59]
	global_load_dwordx4 v[116:119], v4, s[58:59]
	global_load_dwordx4 v[128:131], v0, s[14:15]
	global_load_dwordx4 v[132:135], v0, s[0:1]
.Lp7b_l2:
	s_cmp_lt_u32 s93, 384
	s_cbranch_scc0 .Lp7b_w
	v_add_u32_e32 v0, 320, v40
	v_lshlrev_b32_e32 v0, 4, v0
	v_add_u32_e32 v1, s9, v0
	v_add_u32_e32 v3, s21, v0
	v_add_u32_e32 v2, 0x2c00, v1
	v_add_u32_e32 v4, 0x2c00, v3
	global_load_dwordx4 v[144:147], v1, s[58:59]
	global_load_dwordx4 v[148:151], v2, s[58:59]
	global_load_dwordx4 v[152:155], v3, s[58:59]
	global_load_dwordx4 v[156:159], v4, s[58:59]
	global_load_dwordx4 v[168:171], v0, s[14:15]
	global_load_dwordx4 v[172:175], v0, s[0:1]
; __device__ __forceinline__ unsigned pk2(float lo, float hi) { return f2bf(lo) | (f2bf(hi) << 16); }
; __global__ void __launch_bounds__(512, 2) fwd_megakernel(Args a) {
;     ...
;               f32x4 hg = *(const f32x4*)(HC0 + (size_t)(pm * 2 + rr) * FF2 + col), hv = *(const f32x4*)(HC0 + (size_t)(pm * 2 + rr) * FF2 + FF + col);
;               const f32x4 x1g = *(const f32x4*)(RAWH + (size_t)((pm - 1) * 2 + 1) * FF2 + col), x1v = *(const f32x4*)(RAWH + (size_t)((pm - 1) * 2 + 1) * FF2 + FF + col);
;               const f32x4 x2g = *(const f32x4*)(RAWH + (size_t)((pm - 1) * 2) * FF2 + col), x2v = *(const f32x4*)(RAWH + (size_t)((pm - 1) * 2) * FF2 + FF + col);
;               const f32x4 w0g = *(const f32x4*)(cw + col), w0v = *(const f32x4*)(cw + FF + col), w1g = *(const f32x4*)(cw + FF2 + col), w1v = *(const f32x4*)(cw + FF2 + FF + col);
;               if (rr == 0) { hg += w0g * x2g + w1g * x1g; hv += w0v * x2v + w1v * x1v; } else { hg += w0g * x1g; hv += w0v * x1v; }
;               f32x4 r4;
; #pragma unroll
;               for (int e = 0; e < 4; ++e) r4[e] = hg[e] * __builtin_amdgcn_rcpf(1.0f + __builtin_amdgcn_exp2f(-1.4426950408889634f * hg[e])) * hv[e];
;               v2u w; w.x = pk2(r4[0], r4[1]); w.y = pk2(r4[2], r4[3]);
;               *(v2u*)(ACT + (size_t)(pm * 256 + rr) * FF + col) = w; } }
.Lp7b_w:
	s_waitcnt vmcnt(0)
	v_pk_mul_f32 v[16:17], v[72:73], v[96:97]
	v_pk_mul_f32 v[18:19], v[74:75], v[98:99]
	v_pk_mul_f32 v[22:23], v[94:95], v[86:87]
	v_pk_mul_f32 v[20:21], v[92:93], v[84:85]
	v_pk_fma_f32 v[16:17], v[80:81], v[88:89], v[16:17]
	v_pk_fma_f32 v[18:19], v[82:83], v[90:91], v[18:19]
	v_pk_fma_f32 v[22:23], v[78:79], v[102:103], v[22:23]
	v_pk_fma_f32 v[20:21], v[76:77], v[100:101], v[20:21]
	v_pk_add_f32 v[64:65], v[64:65], v[16:17]
	v_pk_add_f32 v[66:67], v[66:67], v[18:19]
	v_pk_add_f32 v[68:69], v[68:69], v[20:21]
	v_pk_add_f32 v[70:71], v[70:71], v[22:23]
	v_mul_f32_e32 v24, 0xbfb8aa3b, v64
	v_mul_f32_e32 v25, 0xbfb8aa3b, v65
	v_mul_f32_e32 v26, 0xbfb8aa3b, v66
	v_mul_f32_e32 v27, 0xbfb8aa3b, v67
	v_exp_f32_e32 v24, v24
	v_exp_f32_e32 v25, v25
	v_exp_f32_e32 v26, v26
	v_exp_f32_e32 v27, v27
	s_nop 0
	v_add_f32_e32 v24, 1.0, v24
	v_add_f32_e32 v25, 1.0, v25
	v_add_f32_e32 v26, 1.0, v26
	v_add_f32_e32 v27, 1.0, v27
	v_rcp_f32_e32 v24, v24
	v_rcp_f32_e32 v25, v25
	v_rcp_f32_e32 v26, v26
	v_rcp_f32_e32 v27, v27
	s_nop 0
	v_mul_f32_e32 v24, v64, v24
	v_mul_f32_e32 v25, v65, v25
	v_mul_f32_e32 v26, v66, v26
	v_mul_f32_e32 v27, v67, v27
	v_mul_f32_e32 v24, v68, v24
	v_mul_f32_e32 v25, v69, v25
	v_mul_f32_e32 v26, v70, v26
	v_mul_f32_e32 v27, v71, v27
	v_cvt_pk_bf16_f32 v28, v24, v25
	v_cvt_pk_bf16_f32 v29, v26, v27
	v_lshlrev_b32_e32 v0, 3, v40
	v_add_u32_e32 v0, s23, v0
	global_store_dwordx2 v0, v[28:29], s[58:59]
	s_cmp_lt_u32 s93, 192
	s_cbranch_scc0 .Lp7b_c1r
	v_pk_mul_f32 v[16:17], v[112:113], v[136:137]
	v_pk_mul_f32 v[18:19], v[114:115], v[138:139]
	v_pk_mul_f32 v[22:23], v[134:135], v[126:127]
	v_pk_mul_f32 v[20:21], v[132:133], v[124:125]
	v_pk_fma_f32 v[16:17], v[120:121], v[128:129], v[16:17]
	v_pk_fma_f32 v[18:19], v[122:123], v[130:131], v[18:19]
	v_pk_fma_f32 v[22:23], v[118:119], v[142:143], v[22:23]
	v_pk_fma_f32 v[20:21], v[116:117], v[140:141], v[20:21]
	v_pk_add_f32 v[104:105], v[104:105], v[16:17]
	v_pk_add_f32 v[106:107], v[106:107], v[18:19]
	v_pk_add_f32 v[108:109], v[108:109], v[20:21]
	v_pk_add_f32 v[110:111], v[110:111], v[22:23]
	v_mul_f32_e32 v24, 0xbfb8aa3b, v104
	v_mul_f32_e32 v25, 0xbfb8aa3b, v105
	v_mul_f32_e32 v26, 0xbfb8aa3b, v106
	v_mul_f32_e32 v27, 0xbfb8aa3b, v107
	v_exp_f32_e32 v24, v24
	v_exp_f32_e32 v25, v25
	v_exp_f32_e32 v26, v26
	v_exp_f32_e32 v27, v27
	s_nop 0
	v_add_f32_e32 v24, 1.0, v24
	v_add_f32_e32 v25, 1.0, v25
	v_add_f32_e32 v26, 1.0, v26
	v_add_f32_e32 v27, 1.0, v27
	v_rcp_f32_e32 v24, v24
	v_rcp_f32_e32 v25, v25
	v_rcp_f32_e32 v26, v26
	v_rcp_f32_e32 v27, v27
	s_nop 0
	v_mul_f32_e32 v24, v104, v24
	v_mul_f32_e32 v25, v105, v25
	v_mul_f32_e32 v26, v106, v26
	v_mul_f32_e32 v27, v107, v27
	v_mul_f32_e32 v24, v108, v24
	v_mul_f32_e32 v25, v109, v25
	v_mul_f32_e32 v26, v110, v26
	v_mul_f32_e32 v27, v111, v27
	v_cvt_pk_bf16_f32 v28, v24, v25
	v_cvt_pk_bf16_f32 v29, v26, v27
	v_add_u32_e32 v0, 512, v40
	v_lshlrev_b32_e32 v0, 3, v0
	v_add_u32_e32 v0, s23, v0
	global_store_dwordx2 v0, v[28:29], s[58:59]
	s_branch .Lp7b_c2
.Lp7b_c1r:
	v_pk_mul_f32 v[18:19], v[114:115], v[130:131]
	v_pk_mul_f32 v[16:17], v[112:113], v[128:129]
	v_pk_mul_f32 v[22:23], v[118:119], v[134:135]
	v_pk_mul_f32 v[20:21], v[116:117], v[132:133]
	v_pk_add_f32 v[104:105], v[104:105], v[16:17]
	v_pk_add_f32 v[106:107], v[106:107], v[18:19]
	v_pk_add_f32 v[108:109], v[108:109], v[20:21]
	v_pk_add_f32 v[110:111], v[110:111], v[22:23]
	v_mul_f32_e32 v24, 0xbfb8aa3b, v104
	v_mul_f32_e32 v25, 0xbfb8aa3b, v105
	v_mul_f32_e32 v26, 0xbfb8aa3b, v106
	v_mul_f32_e32 v27, 0xbfb8aa3b, v107
	v_exp_f32_e32 v24, v24
	v_exp_f32_e32 v25, v25
	v_exp_f32_e32 v26, v26
	v_exp_f32_e32 v27, v27
	s_nop 0
	v_add_f32_e32 v24, 1.0, v24
	v_add_f32_e32 v25, 1.0, v25
	v_add_f32_e32 v26, 1.0, v26
	v_add_f32_e32 v27, 1.0, v27
	v_rcp_f32_e32 v24, v24
	v_rcp_f32_e32 v25, v25
	v_rcp_f32_e32 v26, v26
	v_rcp_f32_e32 v27, v27
	s_nop 0
	v_mul_f32_e32 v24, v104, v24
	v_mul_f32_e32 v25, v105, v25
	v_mul_f32_e32 v26, v106, v26
	v_mul_f32_e32 v27, v107, v27
	v_mul_f32_e32 v24, v108, v24
	v_mul_f32_e32 v25, v109, v25
	v_mul_f32_e32 v26, v110, v26
	v_mul_f32_e32 v27, v111, v27
	v_cvt_pk_bf16_f32 v28, v24, v25
	v_cvt_pk_bf16_f32 v29, v26, v27
	v_subrev_u32_e32 v0, 192, v40
	v_lshlrev_b32_e32 v0, 3, v0
	v_add_u32_e32 v0, s24, v0
	global_store_dwordx2 v0, v[28:29], s[58:59]
.Lp7b_c2:
	s_cmp_lt_u32 s93, 384
	s_cbranch_scc0 .LBB0_998
	v_pk_mul_f32 v[18:19], v[154:155], v[170:171]
	v_pk_mul_f32 v[16:17], v[152:153], v[168:169]
	v_pk_mul_f32 v[22:23], v[158:159], v[174:175]
	v_pk_mul_f32 v[20:21], v[156:157], v[172:173]
	v_pk_add_f32 v[144:145], v[144:145], v[16:17]
	v_pk_add_f32 v[146:147], v[146:147], v[18:19]
	v_pk_add_f32 v[148:149], v[148:149], v[20:21]
	v_pk_add_f32 v[150:151], v[150:151], v[22:23]
	v_mul_f32_e32 v24, 0xbfb8aa3b, v144
	v_mul_f32_e32 v25, 0xbfb8aa3b, v145
	v_mul_f32_e32 v26, 0xbfb8aa3b, v146
	v_mul_f32_e32 v27, 0xbfb8aa3b, v147
	v_exp_f32_e32 v24, v24
	v_exp_f32_e32 v25, v25
	v_exp_f32_e32 v26, v26
	v_exp_f32_e32 v27, v27
	s_nop 0
	v_add_f32_e32 v24, 1.0, v24
	v_add_f32_e32 v25, 1.0, v25
	v_add_f32_e32 v26, 1.0, v26
	v_add_f32_e32 v27, 1.0, v27
	v_rcp_f32_e32 v24, v24
	v_rcp_f32_e32 v25, v25
	v_rcp_f32_e32 v26, v26
	v_rcp_f32_e32 v27, v27
	s_nop 0
	v_mul_f32_e32 v24, v144, v24
	v_mul_f32_e32 v25, v145, v25
	v_mul_f32_e32 v26, v146, v26
	v_mul_f32_e32 v27, v147, v27
	v_mul_f32_e32 v24, v148, v24
	v_mul_f32_e32 v25, v149, v25
	v_mul_f32_e32 v26, v150, v26
	v_mul_f32_e32 v27, v151, v27
	v_cvt_pk_bf16_f32 v28, v24, v25
	v_cvt_pk_bf16_f32 v29, v26, v27
	v_add_u32_e32 v0, 320, v40
	v_lshlrev_b32_e32 v0, 3, v0
	v_add_u32_e32 v0, s24, v0
	global_store_dwordx2 v0, v[28:29], s[58:59]
	s_branch .LBB0_998
